# PROJ main loop also converted to direct HBM->LDS loads (same swizzled lane-linear image as FFN1)
# speedup vs baseline: 1.0092x; 1.0092x over previous
; DI int TIDX() { int t = threadIdx.x; asm volatile("" : "+v"(t)); return t; }
; #define XCD_LOOP_W(Mt, ntn) const int xcd_ = BIDX() & 7; const int Mx_ = ((Mt) + 7) >> 3; for (int u_ = BIDX() >> 3; u_ < Mx_ * (ntn); u_ += (int)(gridDim.x >> 3))
; template <class BR>
; DI void gemm_tile_w(const h16* __restrict__ A, int lda, const h16* __restrict__ B, int ldb, BR brow, int K, f32x16 (&acc)[4][2], h16* sm) {
;   const int tid = TIDX(), lane = tid & 63, w = tid >> 6, wm = w >> 1, wn = w & 1, r = lane & 31, hh = lane >> 5;
;   const unsigned ao = (unsigned)(tid >> 2) * (unsigned)lda + (unsigned)(tid & 3) * 8u;
;   const unsigned bo0 = (unsigned)brow(tid >> 2) * (unsigned)ldb + (unsigned)(tid & 3) * 8u;
;   const unsigned bo1 = (unsigned)brow((tid >> 2) + 64) * (unsigned)ldb + (unsigned)(tid & 3) * 8u;
;   const h16* ag = A;
;   const h16* bg = B;
;   u32x4 ra0[4], rb0[2], ra1[4], rb1[2];
; #pragma unroll
;   for (int i = 0; i < 4; ++i) ra0[i] = *(const u32x4*)(ag + (ao + (unsigned)i * 64u * (unsigned)lda));
;   rb0[0] = *(const u32x4*)(bg + bo0);
;   rb0[1] = *(const u32x4*)(bg + bo1);
;   ag += 32; bg += 32;
; #pragma unroll
;   for (int i = 0; i < 4; ++i) ra1[i] = *(const u32x4*)(ag + (ao + (unsigned)i * 64u * (unsigned)lda));
;   rb1[0] = *(const u32x4*)(bg + bo0);
;   rb1[1] = *(const u32x4*)(bg + bo1);
;   const int nk = K >> 5;
;   const int wofs = (tid >> 2) * LS2 + (tid & 3) * 8;
; DI void phase_proj(const P& p, int l, char* smem) {
;     ...
;   XCD_LOOP_W(136, 27) {
;     int mt_, nt_;
;     tile_map(u_, Mx_, 27, xcd_, mt_, nt_);
;     if (mt_ >= 136) continue;
;     const int m0 = mt_ * 256, n0 = nt_ * 128;
;     f32x16 acc[4][2];
;     zero_acc_w(acc);
;     gemm_tile_w(hbuf + (size_t)m0 * 1024, 1024, W, 1024, [&](int rr) { return n0 + rr; }, 1024, acc, (h16*)smem);
.LBB0_693:
	s_mul_hi_i32 s0, s36, 0x4bda12f7
	s_lshr_b32 s1, s0, 31
	s_ashr_i32 s0, s0, 6
	s_add_i32 s0, s0, s1
	s_lshl_b32 s4, s0, 3
	s_sub_i32 s1, 17, s4
	s_min_u32 s5, s1, 8
	v_cvt_f32_ubyte0_e32 v0, s5
	v_rcp_iflag_f32_e32 v0, v0
	s_sub_i32 s7, 0, s5
	s_mulk_i32 s0, 0xff28
	s_add_i32 s0, s0, s36
	v_mul_f32_e32 v0, 0x4f7ffffe, v0
	v_cvt_u32_f32_e32 v0, v0
	s_abs_i32 s6, s0
	s_ashr_i32 s1, s0, 31
	v_readfirstlane_b32 s8, v0
	s_mul_i32 s7, s7, s8
	s_mul_hi_u32 s7, s8, s7
	s_add_i32 s8, s8, s7
	s_mul_hi_u32 s7, s6, s8
	s_mul_i32 s8, s7, s5
	s_sub_i32 s6, s6, s8
	s_add_i32 s8, s7, 1
	s_sub_i32 s9, s6, s5
	s_cmp_ge_u32 s6, s5
	s_cselect_b32 s7, s8, s7
	s_cselect_b32 s6, s9, s6
	s_add_i32 s8, s7, 1
	s_cmp_ge_u32 s6, s5
	s_cselect_b32 s6, s8, s7
	s_xor_b32 s6, s6, s1
	s_sub_i32 s1, s6, s1
	s_add_i32 s4, s4, s72
	s_mul_i32 s5, s5, s1
	s_add_i32 s4, s4, s0
	s_sub_i32 s0, s4, s5
	s_cmpk_gt_i32 s0, 0x87
	s_cbranch_scc1 .LBB0_692
	s_lshl_b32 s0, s0, 8
	s_lshl_b32 s10, s1, 7
	s_ashr_i32 s1, s0, 31
	v_mov_b32_e32 v14, v203
	s_lshl_b64 s[4:5], s[0:1], 11
	s_add_u32 s4, s69, s4
	v_ashrrev_i32_e32 v15, 2, v14
	v_lshlrev_b32_e32 v0, 3, v14
	v_and_b32_e32 v16, 24, v0
	v_bfe_u32 v17, v14, 4, 2
	v_lshlrev_b32_e32 v17, 3, v17
	v_xor_b32_e32 v16, v16, v17
	v_add_u32_e32 v10, s10, v15
	s_addc_u32 s5, s24, s5
	v_lshl_or_b32 v0, v15, 10, v16
	v_lshl_or_b32 v210, v10, 10, v16
	v_lshl_add_u64 v[2:3], v[0:1], 1, s[4:5]
	v_add_u32_e32 v204, 0x10000, v0
	v_mov_b32_e32 v205, v1
	v_add_u32_e32 v206, 0x20000, v0
	v_mov_b32_e32 v207, v1
	v_add_u32_e32 v208, 0x30000, v0
	v_mov_b32_e32 v209, v1
	v_add_u32_e32 v212, 0x10000, v210
	v_mov_b32_e32 v211, v1
	s_mov_b64 s[6:7], s[54:55]
	v_mov_b32_e32 v213, v1
	v_lshl_add_u64 v[4:5], v[204:205], 1, s[4:5]
	v_lshl_add_u64 v[6:7], v[206:207], 1, s[4:5]
	v_lshl_add_u64 v[8:9], v[208:209], 1, s[4:5]
	v_lshl_add_u64 v[10:11], v[210:211], 1, s[6:7]
	v_lshl_add_u64 v[12:13], v[212:213], 1, s[6:7]
	v_readfirstlane_b32 s18, v203
	s_nop 3
	s_lshr_b32 s18, s18, 6
	s_lshl_b32 s18, s18, 10
	v_and_b32_e32 v136, 31, v203
	v_bfe_u32 v137, v203, 5, 1
	v_bfe_u32 v138, v203, 2, 2
	v_xor_b32_e32 v137, v137, v138
	v_lshlrev_b32_e32 v137, 4, v137
	v_lshl_or_b32 v136, v136, 6, v137
	v_lshrrev_b32_e32 v138, 7, v203
	v_lshl_add_u32 v130, v138, 13, v136
	v_bfe_u32 v138, v203, 6, 1
	v_lshl_add_u32 v132, v138, 12, v136
	v_xor_b32_e32 v131, 32, v130
	v_xor_b32_e32 v133, 32, v132
	s_add_u32 m0, s18, 0x0
	v_lshl_add_u64 v[134:135], v[0:1], 1, s[4:5]
	global_load_lds_dwordx4 v[134:135], off
	s_add_u32 m0, s18, 0x1000
	v_lshl_add_u64 v[134:135], v[204:205], 1, s[4:5]
	global_load_lds_dwordx4 v[134:135], off
	s_add_u32 m0, s18, 0x2000
	v_lshl_add_u64 v[134:135], v[206:207], 1, s[4:5]
	global_load_lds_dwordx4 v[134:135], off
	s_add_u32 m0, s18, 0x3000
	v_lshl_add_u64 v[134:135], v[208:209], 1, s[4:5]
	global_load_lds_dwordx4 v[134:135], off
	s_add_u32 m0, s18, 0x4000
	v_lshl_add_u64 v[134:135], v[210:211], 1, s[6:7]
	global_load_lds_dwordx4 v[134:135], off
	s_add_u32 m0, s18, 0x5000
	v_lshl_add_u64 v[134:135], v[212:213], 1, s[6:7]
	global_load_lds_dwordx4 v[134:135], off
	s_add_u32 s4, s4, 64
	s_addc_u32 s5, s5, 0
	s_add_u32 s6, s6, 64
	s_addc_u32 s7, s7, 0
	v_mov_b32_e32 v114, 0
	s_mov_b32 s1, 0
	v_mov_b32_e32 v115, v114
	v_mov_b32_e32 v116, v114
	s_waitcnt vmcnt(14)
	v_mov_b32_e32 v117, v114
	v_mov_b32_e32 v118, v114
	v_mov_b32_e32 v119, v114
	s_waitcnt vmcnt(13)
	v_mov_b32_e32 v120, v114
	v_mov_b32_e32 v121, v114
	v_mov_b32_e32 v122, v114
	s_waitcnt vmcnt(12)
	v_mov_b32_e32 v123, v114
	v_mov_b32_e32 v124, v114
	v_mov_b32_e32 v125, v114
	v_mov_b32_e32 v126, v114
	v_mov_b32_e32 v127, v114
	v_mov_b32_e32 v128, v114
	v_mov_b32_e32 v129, v114
	v_mov_b32_e32 v98, v114
	v_mov_b32_e32 v99, v114
	v_mov_b32_e32 v100, v114
	v_mov_b32_e32 v101, v114
	v_mov_b32_e32 v102, v114
	v_mov_b32_e32 v103, v114
	v_mov_b32_e32 v104, v114
	v_mov_b32_e32 v105, v114
	v_mov_b32_e32 v106, v114
	v_mov_b32_e32 v107, v114
	v_mov_b32_e32 v108, v114
	v_mov_b32_e32 v109, v114
	v_mov_b32_e32 v110, v114
	v_mov_b32_e32 v111, v114
	v_mov_b32_e32 v112, v114
	v_mov_b32_e32 v113, v114
	v_mov_b32_e32 v82, v114
	v_mov_b32_e32 v83, v114
	v_mov_b32_e32 v84, v114
	v_mov_b32_e32 v85, v114
	v_mov_b32_e32 v86, v114
	v_mov_b32_e32 v87, v114
	v_mov_b32_e32 v88, v114
	v_mov_b32_e32 v89, v114
	v_mov_b32_e32 v90, v114
	v_mov_b32_e32 v91, v114
	v_mov_b32_e32 v92, v114
	v_mov_b32_e32 v93, v114
	v_mov_b32_e32 v94, v114
	v_mov_b32_e32 v95, v114
	v_mov_b32_e32 v96, v114
	v_mov_b32_e32 v97, v114
	v_mov_b32_e32 v66, v114
	v_mov_b32_e32 v67, v114
	v_mov_b32_e32 v68, v114
	v_mov_b32_e32 v69, v114
	v_mov_b32_e32 v70, v114
	v_mov_b32_e32 v71, v114
	v_mov_b32_e32 v72, v114
	v_mov_b32_e32 v73, v114
	v_mov_b32_e32 v74, v114
	v_mov_b32_e32 v75, v114
	v_mov_b32_e32 v76, v114
	v_mov_b32_e32 v77, v114
	v_mov_b32_e32 v78, v114
	v_mov_b32_e32 v79, v114
	v_mov_b32_e32 v80, v114
	v_mov_b32_e32 v81, v114
	v_mov_b32_e32 v50, v114
	v_mov_b32_e32 v51, v114
	v_mov_b32_e32 v52, v114
	v_mov_b32_e32 v53, v114
	v_mov_b32_e32 v54, v114
	v_mov_b32_e32 v55, v114
	v_mov_b32_e32 v56, v114
	v_mov_b32_e32 v57, v114
	v_mov_b32_e32 v58, v114
	v_mov_b32_e32 v59, v114
	v_mov_b32_e32 v60, v114
	v_mov_b32_e32 v61, v114
	v_mov_b32_e32 v62, v114
	v_mov_b32_e32 v63, v114
	v_mov_b32_e32 v64, v114
	v_mov_b32_e32 v65, v114
	v_mov_b32_e32 v34, v114
	v_mov_b32_e32 v35, v114
	v_mov_b32_e32 v36, v114
	v_mov_b32_e32 v37, v114
	v_mov_b32_e32 v38, v114
	v_mov_b32_e32 v39, v114
	v_mov_b32_e32 v40, v114
	v_mov_b32_e32 v41, v114
	v_mov_b32_e32 v42, v114
	v_mov_b32_e32 v43, v114
	v_mov_b32_e32 v44, v114
	v_mov_b32_e32 v45, v114
	v_mov_b32_e32 v46, v114
	v_mov_b32_e32 v47, v114
	v_mov_b32_e32 v48, v114
	v_mov_b32_e32 v49, v114
	v_mov_b32_e32 v18, v114
	v_mov_b32_e32 v19, v114
	v_mov_b32_e32 v20, v114
	v_mov_b32_e32 v21, v114
	v_mov_b32_e32 v22, v114
	v_mov_b32_e32 v23, v114
	v_mov_b32_e32 v24, v114
	v_mov_b32_e32 v25, v114
	v_mov_b32_e32 v26, v114
	v_mov_b32_e32 v27, v114
	v_mov_b32_e32 v28, v114
	v_mov_b32_e32 v29, v114
	v_mov_b32_e32 v30, v114
	v_mov_b32_e32 v31, v114
	v_mov_b32_e32 v32, v114
	v_mov_b32_e32 v33, v114
	v_mov_b32_e32 v2, v114
	v_mov_b32_e32 v3, v114
	v_mov_b32_e32 v4, v114
	v_mov_b32_e32 v5, v114
	v_mov_b32_e32 v6, v114
	v_mov_b32_e32 v7, v114
	v_mov_b32_e32 v8, v114
	v_mov_b32_e32 v9, v114
	v_mov_b32_e32 v10, v114
	v_mov_b32_e32 v11, v114
	v_mov_b32_e32 v12, v114
	v_mov_b32_e32 v13, v114
	v_mov_b32_e32 v14, v114
	v_mov_b32_e32 v15, v114
	v_mov_b32_e32 v16, v114
	v_mov_b32_e32 v17, v114
	s_waitcnt vmcnt(0)
	s_barrier
; template <class BR>
; DI void gemm_tile_w(const h16* __restrict__ A, int lda, const h16* __restrict__ B, int ldb, BR brow, int K, f32x16 (&acc)[4][2], h16* sm) {
;     ...
;   for (int kt = 0; kt < nk; kt += 2) {
;     WIDE_HALF(ra0, rb0, 0, kt)
;     WIDE_HALF(ra1, rb1, 1, kt + 1)
;   }
.Lpg_stage0:
	ds_read_b128 v[178:181], v130 offset:0
	ds_read_b128 v[182:185], v130 offset:2048
	ds_read_b128 v[186:189], v130 offset:4096
	ds_read_b128 v[190:193], v130 offset:6144
	ds_read_b128 v[194:197], v132 offset:16384
	ds_read_b128 v[198:201], v132 offset:18432
	ds_read_b128 v[216:219], v131 offset:0
	ds_read_b128 v[220:223], v131 offset:2048
	ds_read_b128 v[226:229], v131 offset:4096
	ds_read_b128 v[230:233], v131 offset:6144
	ds_read_b128 v[234:237], v133 offset:16384
	ds_read_b128 v[240:243], v133 offset:18432
	s_cmp_ge_u32 s1, 31
	s_cbranch_scc1 .Lpg_nl0
	s_add_u32 m0, s18, 0x6000
	v_lshl_add_u64 v[134:135], v[0:1], 1, s[4:5]
	global_load_lds_dwordx4 v[134:135], off
	s_add_u32 m0, s18, 0x7000
	v_lshl_add_u64 v[134:135], v[204:205], 1, s[4:5]
	global_load_lds_dwordx4 v[134:135], off
	s_add_u32 m0, s18, 0x8000
	v_lshl_add_u64 v[134:135], v[206:207], 1, s[4:5]
	global_load_lds_dwordx4 v[134:135], off
	s_add_u32 m0, s18, 0x9000
	v_lshl_add_u64 v[134:135], v[208:209], 1, s[4:5]
	global_load_lds_dwordx4 v[134:135], off
	s_add_u32 m0, s18, 0xa000
	v_lshl_add_u64 v[134:135], v[210:211], 1, s[6:7]
	global_load_lds_dwordx4 v[134:135], off
	s_add_u32 m0, s18, 0xb000
	v_lshl_add_u64 v[134:135], v[212:213], 1, s[6:7]
	global_load_lds_dwordx4 v[134:135], off
	s_add_u32 s4, s4, 64
	s_addc_u32 s5, s5, 0
	s_add_u32 s6, s6, 64
	s_addc_u32 s7, s7, 0
.Lpg_nl0:
	s_waitcnt lgkmcnt(6)
	v_mfma_f32_32x32x16_f16 v[114:129], v[178:181], v[194:197], v[114:129]
	v_mfma_f32_32x32x16_f16 v[98:113], v[178:181], v[198:201], v[98:113]
	v_mfma_f32_32x32x16_f16 v[82:97], v[182:185], v[194:197], v[82:97]
	v_mfma_f32_32x32x16_f16 v[66:81], v[182:185], v[198:201], v[66:81]
	v_mfma_f32_32x32x16_f16 v[50:65], v[186:189], v[194:197], v[50:65]
	v_mfma_f32_32x32x16_f16 v[34:49], v[186:189], v[198:201], v[34:49]
	v_mfma_f32_32x32x16_f16 v[18:33], v[190:193], v[194:197], v[18:33]
	v_mfma_f32_32x32x16_f16 v[2:17], v[190:193], v[198:201], v[2:17]
	s_waitcnt lgkmcnt(0)
	v_mfma_f32_32x32x16_f16 v[114:129], v[216:219], v[234:237], v[114:129]
	v_mfma_f32_32x32x16_f16 v[98:113], v[216:219], v[240:243], v[98:113]
	v_mfma_f32_32x32x16_f16 v[82:97], v[220:223], v[234:237], v[82:97]
	v_mfma_f32_32x32x16_f16 v[66:81], v[220:223], v[240:243], v[66:81]
	v_mfma_f32_32x32x16_f16 v[50:65], v[226:229], v[234:237], v[50:65]
	v_mfma_f32_32x32x16_f16 v[34:49], v[226:229], v[240:243], v[34:49]
	v_mfma_f32_32x32x16_f16 v[18:33], v[230:233], v[234:237], v[18:33]
	v_mfma_f32_32x32x16_f16 v[2:17], v[230:233], v[240:243], v[2:17]
	s_add_i32 s1, s1, 1
	s_waitcnt vmcnt(0)
	s_barrier
.Lpg_stage1:
	ds_read_b128 v[178:181], v130 offset:24576
	ds_read_b128 v[182:185], v130 offset:26624
	ds_read_b128 v[186:189], v130 offset:28672
	ds_read_b128 v[190:193], v130 offset:30720
	ds_read_b128 v[194:197], v132 offset:40960
	ds_read_b128 v[198:201], v132 offset:43008
	ds_read_b128 v[216:219], v131 offset:24576
	ds_read_b128 v[220:223], v131 offset:26624
	ds_read_b128 v[226:229], v131 offset:28672
	ds_read_b128 v[230:233], v131 offset:30720
	ds_read_b128 v[234:237], v133 offset:40960
	ds_read_b128 v[240:243], v133 offset:43008
	s_cmp_ge_u32 s1, 31
	s_cbranch_scc1 .Lpg_nl1
	s_add_u32 m0, s18, 0x0
	v_lshl_add_u64 v[134:135], v[0:1], 1, s[4:5]
	global_load_lds_dwordx4 v[134:135], off
	s_add_u32 m0, s18, 0x1000
	v_lshl_add_u64 v[134:135], v[204:205], 1, s[4:5]
	global_load_lds_dwordx4 v[134:135], off
	s_add_u32 m0, s18, 0x2000
	v_lshl_add_u64 v[134:135], v[206:207], 1, s[4:5]
	global_load_lds_dwordx4 v[134:135], off
	s_add_u32 m0, s18, 0x3000
	v_lshl_add_u64 v[134:135], v[208:209], 1, s[4:5]
	global_load_lds_dwordx4 v[134:135], off
	s_add_u32 m0, s18, 0x4000
	v_lshl_add_u64 v[134:135], v[210:211], 1, s[6:7]
	global_load_lds_dwordx4 v[134:135], off
	s_add_u32 m0, s18, 0x5000
	v_lshl_add_u64 v[134:135], v[212:213], 1, s[6:7]
	global_load_lds_dwordx4 v[134:135], off
	s_add_u32 s4, s4, 64
	s_addc_u32 s5, s5, 0
	s_add_u32 s6, s6, 64
	s_addc_u32 s7, s7, 0
.Lpg_nl1:
	s_waitcnt lgkmcnt(6)
	v_mfma_f32_32x32x16_f16 v[114:129], v[178:181], v[194:197], v[114:129]
	v_mfma_f32_32x32x16_f16 v[98:113], v[178:181], v[198:201], v[98:113]
	v_mfma_f32_32x32x16_f16 v[82:97], v[182:185], v[194:197], v[82:97]
	v_mfma_f32_32x32x16_f16 v[66:81], v[182:185], v[198:201], v[66:81]
	v_mfma_f32_32x32x16_f16 v[50:65], v[186:189], v[194:197], v[50:65]
	v_mfma_f32_32x32x16_f16 v[34:49], v[186:189], v[198:201], v[34:49]
	v_mfma_f32_32x32x16_f16 v[18:33], v[190:193], v[194:197], v[18:33]
	v_mfma_f32_32x32x16_f16 v[2:17], v[190:193], v[198:201], v[2:17]
	s_waitcnt lgkmcnt(0)
	v_mfma_f32_32x32x16_f16 v[114:129], v[216:219], v[234:237], v[114:129]
	v_mfma_f32_32x32x16_f16 v[98:113], v[216:219], v[240:243], v[98:113]
	v_mfma_f32_32x32x16_f16 v[82:97], v[220:223], v[234:237], v[82:97]
	v_mfma_f32_32x32x16_f16 v[66:81], v[220:223], v[240:243], v[66:81]
	v_mfma_f32_32x32x16_f16 v[50:65], v[226:229], v[234:237], v[50:65]
	v_mfma_f32_32x32x16_f16 v[34:49], v[226:229], v[240:243], v[34:49]
	v_mfma_f32_32x32x16_f16 v[18:33], v[230:233], v[234:237], v[18:33]
	v_mfma_f32_32x32x16_f16 v[2:17], v[230:233], v[240:243], v[2:17]
	s_add_i32 s1, s1, 1
	s_cmp_ge_u32 s1, 32
	s_cbranch_scc1 .LBB0_700
	s_waitcnt vmcnt(0)
	s_barrier
	s_branch .Lpg_stage0
